# scan chunk loop header: tile loads re-issued right after their LDS writes, LDS scalar reads before the writes, v_cvt_pk_bf16 packs, kernarg pointer load before the barrier
# speedup vs baseline: 1.0041x; 1.0041x over previous
; #define LAS __attribute__((address_space(3)))
; __device__ __forceinline__ unsigned pk2(float lo, float hi) { return f2bf(lo) | (f2bf(hi) << 16); }
; #define SSD_CS(buf_) do { if (w == 0) { float a = rdt * Ah; \
;             _Pragma("unroll") for (int o = 1; o < 64; o <<= 1) { const float v = __shfl_up(a, o); if (lane >= o) a += v; } \
;             ((LAS float*)(L + SS_CS))[(buf_) * 64 + lane] = a; ((LAS float*)(L + SS_DTS))[(buf_) * 64 + lane] = rdt; } } while (0)
; #define SSD_LDT(t0_) do { if (w == 0) rdt = DT[((size_t)b * SEQ + (t0_) + lane) * 64 + h]; } while (0)
; __device__ __forceinline__ void ssd_scan_mfma(const Ctx& c, bf16* X2, const float* DT, const float* a_log, const float* dskip, bool do_store) {
;     ...
;             __syncthreads();
; #pragma unroll
;             for (int e = 0; e < 2; ++e) { const int cc = tid + 512 * e;
;                 *(LAS v4u*)(L + SS_B + (cc >> 4) * 272 + (cc & 15) * 16) = rB[e]; *(LAS v4u*)(L + SS_C + (cc >> 4) * 272 + (cc & 15) * 16) = rC[e]; }
;             *(LAS v4u*)(L + SS_XR + (tid >> 3) * 144 + (tid & 7) * 16) = rXR;
;             { const int sr = tid >> 3, p8 = tid & 7; const float fd = DTS[sr], fw = fd * __expf(CS[63] - CS[sr]);
;               float xv[8];
; #pragma unroll
;               for (int j = 0; j < 4; ++j) { xv[2 * j] = bflo(rXR[j]); xv[2 * j + 1] = bfhi(rXR[j]); }
;               v4u o1, o2; o1.x = pk2(xv[0] * fd, xv[1] * fd); o1.y = pk2(xv[2] * fd, xv[3] * fd); o1.z = pk2(xv[4] * fd, xv[5] * fd); o1.w = pk2(xv[6] * fd, xv[7] * fd);
;               o2.x = pk2(xv[0] * fw, xv[1] * fw); o2.y = pk2(xv[2] * fw, xv[3] * fw); o2.z = pk2(xv[4] * fw, xv[5] * fw); o2.w = pk2(xv[6] * fw, xv[7] * fw);
;               *(LAS v4u*)(L + SS_XD + sr * 144 + p8 * 16) = o1; *(LAS v4u*)(L + SS_XW + sr * 144 + p8 * 16) = o2; }
;             if (ch + 1 < SEQ / 64) { SSD_LOAD(t0 + 64); SSD_CS(cb ^ 1); if (ch + 2 < SEQ / 64) SSD_LDT(t0 + 128); }
.LBB0_469:
	s_and_b32 s96, s63, 1
	s_lshl_b32 s52, s96, 8
	s_add_i32 s65, s52, 0
	s_add_i32 s65, s65, 0x17c00
	s_load_dwordx2 s[4:5], s[68:69], 0x120
	s_xor_b32 s76, s96, 1
	s_mov_b64 s[6:7], s[68:69]
	v_add_u32_e32 v42, s52, v112
	v_mov_b32_e32 v43, s65
	v_lshl_add_u32 v44, v108, 2, s65
	s_waitcnt lgkmcnt(0)
	s_barrier
	ds_read_b32 v42, v42
	ds_read_b32 v43, v43 offset:252
	ds_read_b32 v44, v44
	s_add_u32 s14, s4, 0x234c2000
	s_addc_u32 s15, s5, 0
	v_lshl_add_u64 v[46:47], s[14:15], 0, v[102:103]
	v_lshl_add_u64 v[48:49], s[14:15], 0, v[104:105]
	v_lshl_add_u64 v[50:51], s[4:5], 0, v[100:101]
	s_waitcnt vmcnt(6)
	ds_write_b128 v130, v[30:33]
	s_waitcnt vmcnt(5)
	ds_write_b128 v130, v[26:29] offset:17408
	global_load_dwordx4 v[30:33], v[46:47], off
	global_load_dwordx4 v[26:29], v[46:47], off offset:2048
	s_waitcnt vmcnt(6)
	ds_write_b128 v131, v[38:41]
	s_waitcnt vmcnt(5)
	ds_write_b128 v131, v[34:37] offset:17408
	global_load_dwordx4 v[38:41], v[48:49], off
	global_load_dwordx4 v[34:37], v[48:49], off offset:2048
	s_waitcnt vmcnt(6)
	ds_write_b128 v132, v[22:25] offset:34816
	v_lshlrev_b32_e32 v52, 16, v22
	v_lshlrev_b32_e32 v53, 16, v23
	v_and_b32_e32 v56, 0xffff0000, v22
	v_and_b32_e32 v57, 0xffff0000, v23
	v_lshlrev_b32_e32 v58, 16, v24
	v_lshlrev_b32_e32 v59, 16, v25
	v_and_b32_e32 v60, 0xffff0000, v24
	v_and_b32_e32 v61, 0xffff0000, v25
	global_load_dwordx4 v[22:25], v[50:51], off
	s_waitcnt lgkmcnt(5)
	v_sub_f32_e32 v43, v43, v44
	v_mul_f32_e32 v43, 0x3fb8aa3b, v43
	v_exp_f32_e32 v43, v43
	v_pk_mul_f32 v[62:63], v[42:43], v[52:53] op_sel_hi:[0,1]
	v_mul_f32_e32 v44, v42, v43
	v_pk_mul_f32 v[64:65], v[42:43], v[56:57] op_sel_hi:[0,1]
	v_pk_mul_f32 v[66:67], v[42:43], v[58:59] op_sel_hi:[0,1]
	v_pk_mul_f32 v[142:143], v[42:43], v[60:61] op_sel_hi:[0,1]
	v_pk_mul_f32 v[144:145], v[44:45], v[52:53] op_sel_hi:[0,1]
	v_pk_mul_f32 v[146:147], v[44:45], v[56:57] op_sel_hi:[0,1]
	v_pk_mul_f32 v[148:149], v[44:45], v[58:59] op_sel_hi:[0,1]
	v_pk_mul_f32 v[150:151], v[44:45], v[60:61] op_sel_hi:[0,1]
	v_cvt_pk_bf16_f32 v152, v62, v64
	v_cvt_pk_bf16_f32 v153, v63, v65
	v_cvt_pk_bf16_f32 v154, v66, v142
	v_cvt_pk_bf16_f32 v155, v67, v143
	v_cvt_pk_bf16_f32 v156, v144, v146
	v_cvt_pk_bf16_f32 v157, v145, v147
	v_cvt_pk_bf16_f32 v158, v148, v150
	v_cvt_pk_bf16_f32 v159, v149, v151
	ds_write_b128 v132, v[152:155] offset:44032
	ds_write_b128 v132, v[156:159] offset:53248
	s_and_b64 vcc, exec, s[50:51]
	s_cbranch_vccnz .LBB0_471
	v_mul_f32_e64 v42, v93, -v138
	s_nop 1
	v_add_f32_dpp v42, v42, v42 row_shr:1 row_mask:0xf bank_mask:0xf
	s_nop 1
	v_add_f32_dpp v42, v42, v42 row_shr:2 row_mask:0xf bank_mask:0xf
	s_nop 1
	v_add_f32_dpp v42, v42, v42 row_shr:4 row_mask:0xf bank_mask:0xf
	s_nop 1
	v_add_f32_dpp v42, v42, v42 row_shr:8 row_mask:0xf bank_mask:0xf
	s_nop 1
	v_add_f32_dpp v42, v42, v42 row_bcast:15 row_mask:0xa bank_mask:0xf
	s_nop 1
	v_add_f32_dpp v42, v42, v42 row_bcast:31 row_mask:0xc bank_mask:0xf
	s_nop 1
	v_lshl_or_b32 v43, s76, 8, v109
	v_add_u32_e32 v43, 0, v43
	v_add_u32_e32 v44, 0x17c00, v43
	ds_write_b32 v44, v42
	v_add_u32_e32 v42, 0x17e00, v43
	ds_write_b32 v42, v93
